# speedup vs baseline: 1.0087x; 1.0008x over previous
; #define LAS __attribute__((address_space(3)))
; #define ATT_KRD(KOFF, DLO, DHI) do { _Pragma("unroll") for (int d0 = (DLO); d0 < (DHI); ++d0) { kf[2 * d0] = *(const LAS bf16x8*)(lds + (KOFF) + kr + 2 * d0 * KCH); kf[2 * d0 + 1] = *(const LAS bf16x8*)(lds + (KOFF) + kr + 2 * d0 * KCH + 512); } } while (0)
; #define ATT_SB() __builtin_amdgcn_sched_barrier(0)
; #define ATT_EXP2(J) do { float e0_, e1_; if ((J) < 8) { e0_ = __builtin_amdgcn_exp2f(p0[2 * (J)]); e1_ = __builtin_amdgcn_exp2f(p0[2 * (J) + 1]); } else { e0_ = __builtin_amdgcn_exp2f(p1[2 * (J) - 16]); e1_ = __builtin_amdgcn_exp2f(p1[2 * (J) - 15]); } \
;                 sum += e0_; sum += e1_; asm volatile("" : "+v"(sum)); pkn[(J) >> 2][(J) & 3] = cvtpk_s(e0_, e1_); } while (0)
; __device__ __forceinline__ void attn_unit(LAS unsigned char* lds, bf16_t* Qm, const bf16_t* __restrict__ Kb, const bf16_t* __restrict__ Vt,
;                                           int b, int h, int qb, int lgS, float lam, float oscale, const float* __restrict__ subg, float* stash) {
;     ...
;             for (int ks = 1; ks < 4; ++ks) {
; #pragma unroll
;                 for (int blk = 0; blk < 4; ++blk) {
;                     const int gi = (ks - 1) * 4 + blk;
;                     if (blk == 0 && ks < 3) {
; #pragma unroll
;                         for (int b2 = 0; b2 < 4; ++b2) { const bf16x8 v_ = *(const LAS bf16x8*)(lds + vs0 + vr + b2 * 32 * VP + (ks + 1) * 32); if (ks & 1) vfa[b2] = v_; else vfb[b2] = v_; }
;                     }
;                     o[blk] = __builtin_amdgcn_mfma_f32_32x32x16_bf16((ks & 1) ? vfb[blk] : vfa[blk], __builtin_bit_cast(bf16x8, pk[ks]), o[blk], 0, 0, 0);
;                     ATT_EXP2(gi);
;                     if (gi < 4) ATT_EXP2(12 + gi);
;                     ATT_SB();
;                 }
;             }
;     ...
;             lrun += sum;
; #pragma unroll
;             for (int j = 0; j < 4; ++j) pk[j] = pkn[j];
;             if (t + 2 < NT) ATT_KRD(kq2, 0, 1);
; #pragma unroll
;             for (int b2 = 0; b2 < 4; ++b2) vfa[b2] = *(const LAS bf16x8*)(lds + vs1 + vr + b2 * 32 * VP);
;             ATT_SB();
;             { const int tmp = vs0; vs0 = vs1; vs1 = vs2; vs2 = tmp; }
;             { const int tmp = kq0; kq0 = kq1; kq1 = kq2; kq2 = tmp; }
;             __syncthreads();
.LBB0_342:
	v_exp_f32_e32 v96, v96
	s_waitcnt lgkmcnt(3)
	v_mfma_f32_32x32x16_bf16 v[0:15], v[216:219], v[180:183], v[0:15]
	v_exp_f32_e32 v97, v97
	ds_read_b128 v[192:195], v251 offset:25408
	ds_read_b128 v[196:199], v251 offset:30016
	ds_read_b128 v[188:191], v251 offset:34624
	ds_read_b128 v[184:187], v251 offset:39232
	v_exp_f32_e32 v88, v88
	v_add_f32_e32 v200, 0, v96
	v_exp_f32_e32 v89, v89
	v_add_f32_e32 v200, v97, v200
	s_nop 0
	v_add_f32_e32 v200, v88, v200
	v_add_f32_e32 v200, v89, v200
	v_exp_f32_e32 v98, v98
	s_waitcnt lgkmcnt(6)
	v_mfma_f32_32x32x16_bf16 v[48:63], v[212:215], v[180:183], v[48:63]
	v_exp_f32_e32 v99, v99
	v_exp_f32_e32 v90, v90
	v_add_f32_e32 v200, v98, v200
	v_exp_f32_e32 v91, v91
	v_add_f32_e32 v200, v99, v200
	s_nop 0
	v_add_f32_e32 v200, v90, v200
	v_add_f32_e32 v200, v91, v200
	v_exp_f32_e32 v100, v100
	s_waitcnt lgkmcnt(5)
	v_mfma_f32_32x32x16_bf16 v[32:47], v[208:211], v[180:183], v[32:47]
	v_exp_f32_e32 v101, v101
	v_exp_f32_e32 v92, v92
	v_add_f32_e32 v200, v100, v200
	v_exp_f32_e32 v93, v93
	v_add_f32_e32 v200, v101, v200
	s_nop 0
	v_add_f32_e32 v200, v92, v200
	v_add_f32_e32 v200, v93, v200
	v_exp_f32_e32 v102, v102
	s_waitcnt lgkmcnt(4)
	v_mfma_f32_32x32x16_bf16 v[16:31], v[204:207], v[180:183], v[16:31]
	v_exp_f32_e32 v103, v103
	v_exp_f32_e32 v94, v94
	v_add_f32_e32 v180, v102, v200
	v_exp_f32_e32 v95, v95
	v_add_f32_e32 v180, v103, v180
	s_nop 0
	v_add_f32_e32 v180, v94, v180
	v_add_f32_e32 v212, v95, v180
	s_waitcnt lgkmcnt(3)
	v_mfma_f32_32x32x16_bf16 v[0:15], v[192:195], v[172:175], v[0:15]
	ds_read_b128 v[180:183], v251 offset:25440
	ds_read_b128 v[200:203], v251 offset:30048
	ds_read_b128 v[204:207], v251 offset:34656
	ds_read_b128 v[208:211], v251 offset:39264
	v_exp_f32_e32 v104, v104
	v_exp_f32_e32 v105, v105
	v_add_f32_e32 v156, v104, v212
	v_add_f32_e32 v156, v105, v156
	v_add_u32_e32 v251, s25, v220
	v_add_u32_e32 v160, s50, v235
	s_cmp_eq_u32 s98, 0
	s_cbranch_scc1 .Lmy_skip_m
	s_waitcnt lgkmcnt(0)
	s_barrier
.Lmy_skip_m:
	s_waitcnt lgkmcnt(6)
	v_mfma_f32_32x32x16_bf16 v[48:63], v[196:199], v[172:175], v[48:63]
	ds_read_b128 v[192:195], v251 offset:29952
	v_exp_f32_e32 v106, v106
	v_exp_f32_e32 v107, v107
	v_add_f32_e32 v156, v106, v156
	v_add_f32_e32 v156, v107, v156
	s_waitcnt lgkmcnt(6)
	v_mfma_f32_32x32x16_bf16 v[32:47], v[188:191], v[172:175], v[32:47]
	ds_read_b128 v[196:199], v251 offset:25344
	v_exp_f32_e32 v108, v108
	v_exp_f32_e32 v109, v109
	v_add_f32_e32 v156, v108, v156
	v_add_f32_e32 v156, v109, v156
	s_waitcnt lgkmcnt(6)
	v_mfma_f32_32x32x16_bf16 v[16:31], v[184:187], v[172:175], v[16:31]
	ds_read_b128 v[188:191], v251 offset:34560
	ds_read_b128 v[212:215], v160 offset:4224
	ds_read_b128 v[216:219], v160 offset:4736
	v_exp_f32_e32 v110, v110
	v_exp_f32_e32 v111, v111
	v_add_f32_e32 v156, v110, v156
	v_add_f32_e32 v156, v111, v156
	s_waitcnt lgkmcnt(8)
	v_mfma_f32_32x32x16_bf16 v[0:15], v[180:183], v[164:167], v[0:15]
	ds_read_b128 v[184:187], v251 offset:39168
	ds_read_b128 v[222:225], v160 offset:6336
	ds_read_b128 v[240:243], v160 offset:6848
	v_exp_f32_e32 v80, v80
	v_exp_f32_e32 v81, v81
	v_add_f32_e32 v156, v80, v156
	v_add_f32_e32 v156, v81, v156
	v_cvt_pk_bf16_f32 v180, v104, v105
	v_cvt_pk_bf16_f32 v181, v106, v107
	v_cvt_pk_bf16_f32 v182, v108, v109
	v_cvt_pk_bf16_f32 v183, v110, v111
	s_waitcnt lgkmcnt(10)
	v_mfma_f32_32x32x16_bf16 v[48:63], v[200:203], v[164:167], v[48:63]
	v_exp_f32_e32 v82, v82
	v_exp_f32_e32 v83, v83
	v_add_f32_e32 v156, v82, v156
	v_add_f32_e32 v156, v83, v156
	v_cvt_pk_bf16_f32 v200, v96, v97
	v_cvt_pk_bf16_f32 v201, v98, v99
	v_cvt_pk_bf16_f32 v202, v100, v101
	v_cvt_pk_bf16_f32 v203, v102, v103
	v_cvt_pk_bf16_f32 v172, v80, v81
	s_waitcnt lgkmcnt(9)
	v_mfma_f32_32x32x16_bf16 v[32:47], v[204:207], v[164:167], v[32:47]
	ds_read_b128 v[204:207], v160 offset:2112
	v_exp_f32_e32 v84, v84
	v_exp_f32_e32 v85, v85
	v_add_f32_e32 v156, v84, v156
	v_add_f32_e32 v156, v85, v156
	v_cvt_pk_bf16_f32 v173, v82, v83
	s_waitcnt lgkmcnt(9)
	v_mfma_f32_32x32x16_bf16 v[16:31], v[208:211], v[164:167], v[16:31]
	ds_read_b128 v[208:211], v160 offset:2624
	v_exp_f32_e32 v86, v86
	v_exp_f32_e32 v87, v87
	v_add_f32_e32 v156, v86, v156
	v_add_f32_e32 v156, v87, v156
	v_add_f32_e32 v249, v249, v156
	ds_read_b128 v[156:159], v160
	ds_read_b128 v[160:163], v160 offset:512
	v_cvt_pk_bf16_f32 v174, v84, v85
	v_cvt_pk_bf16_f32 v175, v86, v87
	v_cvt_pk_bf16_f32 v164, v88, v89
	v_cvt_pk_bf16_f32 v165, v90, v91
	v_cvt_pk_bf16_f32 v166, v92, v93
	v_cvt_pk_bf16_f32 v167, v94, v95
	s_add_i32 s57, s57, 1
	s_add_i32 s90, s90, 64
	s_mov_b64 s[28:29], 0x10000
	v_lshl_add_u64 v[238:239], v[238:239], 0, s[28:29]
	s_waitcnt lgkmcnt(0)
	s_cmp_lg_u32 s98, 0
	s_cbranch_scc1 .Lmy_skip_e
	s_barrier
